# gelud + P2 sample GEMM: h1 sample rows tile-major and all fragment loads of a task up front (both halves of P2 shortened together)
# baseline (speedup 1.0000x reference)
; __device__ __forceinline__ void st_bf16x8(bf16_t* p, const f32x4 a, const f32x4 b) { uint4 o; o.x = cvt_pk_bf16(a[0], a[1]); o.y = cvt_pk_bf16(a[2], a[3]); o.z = cvt_pk_bf16(b[0], b[1]); o.w = cvt_pk_bf16(b[2], b[3]); *(uint4*)p = o; }
;     ...
;         for (int q = 0; q < 4; ++q) { float ss = 0.f;
; #pragma unroll
;             for (int i = 0; i < 4; ++i) ss += v[q][i][0] * v[q][i][0] + v[q][i][1] * v[q][i][1] + v[q][i][2] * v[q][i][2] + v[q][i][3] * v[q][i][3];
; #pragma unroll
;             for (int o = 1; o < 64; o <<= 1) ss += __shfl_xor(ss, o);
;             rs[q] = rsqrtf(ss * (1.f / DM) + EPS); }
; #pragma unroll
;         for (int q = 0; q < 4; ++q) { const int row = rowb + q * nw;
;             if (row < r1) { const float* mb = mod + (size_t)batch_of(row) * NMOD;
; #pragma unroll
;                 for (int h = 0; h < 2; ++h) { const int c = h * 512 + lane * 8;
;                     const f32x4 y0 = v[q][2 * h] * rs[q] * gv[2 * h], y1 = v[q][2 * h + 1] * rs[q] * gv[2 * h + 1];
;                     if (FINAL) { *(f32x4*)(p.out + (size_t)row * DM + c) = y0; *(f32x4*)(p.out + (size_t)row * DM + c + 4) = y1; }
;                     else { if (WT) st_wt_bf16x8(H + (size_t)row * DM + c, y0 * (*(const f32x4*)(mb + sc_off + c) + 1.f) + *(const f32x4*)(mb + sh_off + c),
;                                                              y1 * (*(const f32x4*)(mb + sc_off + c + 4) + 1.f) + *(const f32x4*)(mb + sh_off + c + 4)); else st_bf16x8(H + (size_t)row * DM + c, y0 * (*(const f32x4*)(mb + sc_off + c) + 1.f) + *(const f32x4*)(mb + sh_off + c),
;                                                              y1 * (*(const f32x4*)(mb + sc_off + c + 4) + 1.f) + *(const f32x4*)(mb + sh_off + c + 4)); } } } }
.LBB0_142:
	s_or_b64 exec, exec, s[64:65]
	s_waitcnt vmcnt(2)
	v_mov_b32_e32 v106, v61
	v_mov_b32_e32 v107, v57
	v_mov_b32_e32 v104, v60
	v_mov_b32_e32 v105, v56
	v_pk_mul_f32 v[106:107], v[106:107], v[106:107]
	s_waitcnt vmcnt(0)
	v_mov_b32_e32 v108, v53
	v_pk_fma_f32 v[104:105], v[104:105], v[104:105], v[106:107]
	v_mov_b32_e32 v106, v62
	v_mov_b32_e32 v107, v58
	v_pk_fma_f32 v[104:105], v[106:107], v[106:107], v[104:105]
	v_mov_b32_e32 v106, v63
	v_mov_b32_e32 v107, v59
	v_mov_b32_e32 v109, v49
	v_pk_fma_f32 v[104:105], v[106:107], v[106:107], v[104:105]
	v_mov_b32_e32 v106, v52
	v_mov_b32_e32 v107, v48
	v_pk_mul_f32 v[108:109], v[108:109], v[108:109]
	v_ashrrev_i32_e32 v79, 11, v67
	v_pk_fma_f32 v[106:107], v[106:107], v[106:107], v[108:109]
	v_mov_b32_e32 v108, v54
	v_mov_b32_e32 v109, v50
	v_pk_fma_f32 v[106:107], v[108:109], v[108:109], v[106:107]
	v_mov_b32_e32 v108, v55
	v_mov_b32_e32 v109, v51
	v_pk_fma_f32 v[122:123], v[108:109], v[108:109], v[106:107]
	v_add_u32_e32 v106, 0xffffc008, v67
	v_cndmask_b32_e64 v79, v106, v79, s[6:7]
	v_mov_b64_e32 v[106:107], s[16:17]
	v_mad_i64_i32 v[114:115], s[6:7], v79, s13, v[106:107]
	v_lshl_add_u64 v[126:127], v[114:115], 0, s[10:11]
	v_lshl_add_u64 v[110:111], v[126:127], 0, v[80:81]
	global_load_dwordx4 v[106:109], v[110:111], off offset:16
	s_nop 0
	global_load_dwordx4 v[110:113], v[110:111], off
	v_lshl_add_u64 v[128:129], v[114:115], 0, v[80:81]
	global_load_dwordx4 v[114:117], v[128:129], off offset:16
	global_load_dwordx4 v[118:121], v[128:129], off
	v_pk_mul_f32 v[124:125], v[92:93], v[92:93]
	v_pk_mul_f32 v[130:131], v[86:87], v[86:87]
	v_pk_fma_f32 v[124:125], v[24:25], v[24:25], v[124:125]
	v_pk_fma_f32 v[130:131], v[20:21], v[20:21], v[130:131]
	v_pk_fma_f32 v[124:125], v[26:27], v[26:27], v[124:125]
	v_pk_fma_f32 v[130:131], v[22:23], v[22:23], v[130:131]
	v_pk_fma_f32 v[124:125], v[88:89], v[88:89], v[124:125]
	v_pk_fma_f32 v[130:131], v[84:85], v[84:85], v[130:131]
	v_mov_b32_e32 v132, v104
	v_mov_b32_e32 v133, v124
	v_mov_b32_e32 v124, v105
	v_pk_add_f32 v[104:105], v[132:133], v[124:125]
	v_mov_b32_e32 v124, v122
	v_mov_b32_e32 v125, v130
	v_pk_add_f32 v[104:105], v[104:105], v[124:125]
	v_mov_b32_e32 v130, v123
	v_pk_add_f32 v[104:105], v[104:105], v[130:131]
	ds_bpermute_b32 v122, v225, v104
	ds_bpermute_b32 v123, v225, v105
	s_waitcnt lgkmcnt(0)
	v_pk_add_f32 v[104:105], v[104:105], v[122:123]
	ds_bpermute_b32 v122, v226, v104
	ds_bpermute_b32 v123, v226, v105
	s_waitcnt lgkmcnt(0)
	v_pk_add_f32 v[104:105], v[104:105], v[122:123]
	ds_bpermute_b32 v122, v227, v104
	ds_bpermute_b32 v123, v227, v105
	s_waitcnt lgkmcnt(0)
	v_pk_add_f32 v[104:105], v[104:105], v[122:123]
	ds_bpermute_b32 v122, v228, v104
	ds_bpermute_b32 v123, v228, v105
	s_waitcnt lgkmcnt(0)
	v_pk_add_f32 v[104:105], v[104:105], v[122:123]
	ds_bpermute_b32 v122, v229, v104
	ds_bpermute_b32 v123, v229, v105
	s_waitcnt lgkmcnt(0)
	v_pk_add_f32 v[104:105], v[104:105], v[122:123]
	ds_bpermute_b32 v122, v230, v104
	ds_bpermute_b32 v123, v230, v105
	s_waitcnt lgkmcnt(0)
	v_pk_add_f32 v[104:105], v[104:105], v[122:123]
	s_nop 0
	v_pk_fma_f32 v[104:105], v[104:105], s[14:15], v[82:83] op_sel_hi:[1,0,0]
	v_and_b32_e32 v122, -16, v64
	v_lshlrev_b32_e32 v122, 11, v122
	v_and_b32_e32 v123, 15, v64
	v_lshl_add_u32 v122, v123, 4, v122
	v_lshl_add_u32 v122, v70, 4, v122
	v_mov_b32_e32 v123, 0
	v_lshl_add_u64 v[122:123], s[58:59], 0, v[122:123]
	v_mul_f32_e32 v79, 0x4b800000, v104
	v_cmp_gt_f32_e64 s[6:7], s15, v104
	s_waitcnt vmcnt(3)
	v_pk_add_f32 v[108:109], v[108:109], 1.0 op_sel_hi:[1,0]
	v_cndmask_b32_e64 v79, v104, v79, s[6:7]
	v_rsq_f32_e32 v79, v79
	s_waitcnt vmcnt(2)
	v_pk_add_f32 v[110:111], v[110:111], 1.0 op_sel_hi:[1,0]
	v_pk_add_f32 v[112:113], v[112:113], 1.0 op_sel_hi:[1,0]
	v_pk_add_f32 v[106:107], v[106:107], 1.0 op_sel_hi:[1,0]
	v_mul_f32_e32 v104, 0x45800000, v79
	v_cndmask_b32_e64 v104, v79, v104, s[6:7]
	v_pk_mul_f32 v[60:61], v[60:61], v[104:105] op_sel_hi:[1,0]
	v_pk_mul_f32 v[62:63], v[62:63], v[104:105] op_sel_hi:[1,0]
	v_pk_mul_f32 v[60:61], v[4:5], v[60:61]
	v_pk_mul_f32 v[58:59], v[58:59], v[104:105] op_sel_hi:[1,0]
	v_pk_mul_f32 v[56:57], v[56:57], v[104:105] op_sel_hi:[1,0]
	v_pk_mul_f32 v[62:63], v[6:7], v[62:63]
	v_pk_mul_f32 v[56:57], v[0:1], v[56:57]
	v_pk_mul_f32 v[58:59], v[2:3], v[58:59]
	s_waitcnt vmcnt(0)
; __device__ __forceinline__ void st_bf16x8(bf16_t* p, const f32x4 a, const f32x4 b) { uint4 o; o.x = cvt_pk_bf16(a[0], a[1]); o.y = cvt_pk_bf16(a[2], a[3]); o.z = cvt_pk_bf16(b[0], b[1]); o.w = cvt_pk_bf16(b[2], b[3]); *(uint4*)p = o; }
;     ...
;         for (int q = 0; q < 4; ++q) { float ss = 0.f;
; #pragma unroll
;             for (int i = 0; i < 4; ++i) ss += v[q][i][0] * v[q][i][0] + v[q][i][1] * v[q][i][1] + v[q][i][2] * v[q][i][2] + v[q][i][3] * v[q][i][3];
; #pragma unroll
;             for (int o = 1; o < 64; o <<= 1) ss += __shfl_xor(ss, o);
;             rs[q] = rsqrtf(ss * (1.f / DM) + EPS); }
; #pragma unroll
;         for (int q = 0; q < 4; ++q) { const int row = rowb + q * nw;
;             if (row < r1) { const float* mb = mod + (size_t)batch_of(row) * NMOD;
; #pragma unroll
;                 for (int h = 0; h < 2; ++h) { const int c = h * 512 + lane * 8;
;                     const f32x4 y0 = v[q][2 * h] * rs[q] * gv[2 * h], y1 = v[q][2 * h + 1] * rs[q] * gv[2 * h + 1];
;                     if (FINAL) { *(f32x4*)(p.out + (size_t)row * DM + c) = y0; *(f32x4*)(p.out + (size_t)row * DM + c + 4) = y1; }
;                     else { if (WT) st_wt_bf16x8(H + (size_t)row * DM + c, y0 * (*(const f32x4*)(mb + sc_off + c) + 1.f) + *(const f32x4*)(mb + sh_off + c),
;                                                              y1 * (*(const f32x4*)(mb + sc_off + c + 4) + 1.f) + *(const f32x4*)(mb + sh_off + c + 4)); else st_bf16x8(H + (size_t)row * DM + c, y0 * (*(const f32x4*)(mb + sc_off + c) + 1.f) + *(const f32x4*)(mb + sh_off + c),
;                                                              y1 * (*(const f32x4*)(mb + sc_off + c + 4) + 1.f) + *(const f32x4*)(mb + sh_off + c + 4)); } } } }
	v_pk_fma_f32 v[60:61], v[60:61], v[110:111], v[118:119]
	v_add_co_u32_e64 v118, s[6:7], s66, v122
	v_pk_fma_f32 v[62:63], v[62:63], v[112:113], v[120:121]
	v_pk_fma_f32 v[108:109], v[58:59], v[108:109], v[116:117]
	v_pk_fma_f32 v[58:59], v[56:57], v[106:107], v[114:115]
	v_cvt_pk_bf16_f32 v56, v60, v61
	v_cvt_pk_bf16_f32 v57, v62, v63
	v_addc_co_u32_e64 v119, s[6:7], 0, v123, s[6:7]
	v_mov_b32_e32 v79, v81
	v_cvt_pk_bf16_f32 v58, v58, v59
	v_cvt_pk_bf16_f32 v59, v108, v109
	global_store_dwordx4 v[118:119], v[56:59], off sc1
	v_pk_mul_f32 v[54:55], v[54:55], v[104:105] op_sel_hi:[1,0]
	v_pk_mul_f32 v[52:53], v[52:53], v[104:105] op_sel_hi:[1,0]
	v_lshl_add_u64 v[56:57], v[126:127], 0, v[78:79]
	global_load_dwordx4 v[60:63], v[56:57], off
	global_load_dwordx4 v[106:109], v[128:129], off offset:2048
	global_load_dwordx4 v[110:113], v[56:57], off offset:16
	global_load_dwordx4 v[114:117], v[128:129], off offset:2064
	v_mul_f32_e32 v56, v45, v45
	v_mul_f32_e32 v57, v41, v41
	v_fmac_f32_e32 v56, v44, v44
	v_fmac_f32_e32 v57, v40, v40
	v_fmac_f32_e32 v56, v46, v46
	v_fmac_f32_e32 v57, v42, v42
	v_fmac_f32_e32 v56, v47, v47
	v_fmac_f32_e32 v57, v43, v43
	v_add_f32_e32 v56, v57, v56
	v_mul_f32_e32 v57, v37, v37
	v_fmac_f32_e32 v57, v36, v36
	v_fmac_f32_e32 v57, v38, v38
	v_fmac_f32_e32 v57, v39, v39
	v_add_f32_e32 v56, v57, v56
	v_mul_f32_e32 v57, v33, v33
	v_fmac_f32_e32 v57, v32, v32
	v_fmac_f32_e32 v57, v34, v34
	v_fmac_f32_e32 v57, v35, v35
	v_add_f32_e32 v120, v57, v56
	v_pk_mul_f32 v[56:57], v[102:103], v[102:103]
	v_pk_mul_f32 v[58:59], v[94:95], v[94:95]
	v_pk_fma_f32 v[56:57], v[28:29], v[28:29], v[56:57]
	v_pk_fma_f32 v[58:59], v[16:17], v[16:17], v[58:59]
	v_pk_fma_f32 v[56:57], v[30:31], v[30:31], v[56:57]
	v_pk_fma_f32 v[58:59], v[18:19], v[18:19], v[58:59]
	v_pk_fma_f32 v[56:57], v[100:101], v[100:101], v[56:57]
	v_pk_fma_f32 v[58:59], v[96:97], v[96:97], v[58:59]
	v_add_f32_e32 v56, v56, v57
	v_add_f32_e32 v56, v59, v56
	v_add_f32_e32 v56, v58, v56
	ds_bpermute_b32 v121, v225, v120
	ds_bpermute_b32 v57, v225, v56
	v_pk_mul_f32 v[52:53], v[12:13], v[52:53]
	v_pk_mul_f32 v[54:55], v[14:15], v[54:55]
	v_pk_mul_f32 v[50:51], v[50:51], v[104:105] op_sel_hi:[1,0]
	s_waitcnt lgkmcnt(1)
	v_add_f32_e32 v58, v120, v121
	s_waitcnt lgkmcnt(0)
	v_add_f32_e32 v56, v56, v57
	ds_bpermute_b32 v59, v226, v58
	ds_bpermute_b32 v57, v226, v56
	v_pk_mul_f32 v[48:49], v[48:49], v[104:105] op_sel_hi:[1,0]
	v_pk_mul_f32 v[50:51], v[10:11], v[50:51]
	v_pk_mul_f32 v[48:49], v[8:9], v[48:49]
	s_waitcnt lgkmcnt(1)
	v_add_f32_e32 v58, v58, v59
	s_waitcnt lgkmcnt(0)
	v_add_f32_e32 v56, v56, v57
	ds_bpermute_b32 v59, v227, v58
	ds_bpermute_b32 v57, v227, v56
	v_cmp_gt_f32_e64 s[6:7], s15, v105
	s_waitcnt lgkmcnt(1)
	v_add_f32_e32 v58, v58, v59
	s_waitcnt lgkmcnt(0)
	v_add_f32_e32 v56, v56, v57
	ds_bpermute_b32 v59, v228, v58
	ds_bpermute_b32 v57, v228, v56
	s_waitcnt lgkmcnt(1)
	v_add_f32_e32 v58, v58, v59
	s_waitcnt lgkmcnt(0)
	v_add_f32_e32 v56, v56, v57
	ds_bpermute_b32 v59, v229, v58
	ds_bpermute_b32 v57, v229, v56
	s_waitcnt lgkmcnt(1)
	v_add_f32_e32 v58, v58, v59
	s_waitcnt lgkmcnt(0)
	v_add_f32_e32 v56, v56, v57
	ds_bpermute_b32 v59, v230, v58
	ds_bpermute_b32 v57, v230, v56
	s_waitcnt vmcnt(3)
	v_pk_add_f32 v[62:63], v[62:63], 1.0 op_sel_hi:[1,0]
	v_pk_add_f32 v[60:61], v[60:61], 1.0 op_sel_hi:[1,0]
	s_waitcnt vmcnt(2)
	v_pk_fma_f32 v[54:55], v[54:55], v[62:63], v[108:109]
	v_pk_fma_f32 v[52:53], v[52:53], v[60:61], v[106:107]
	s_waitcnt vmcnt(1)
	v_pk_add_f32 v[60:61], v[112:113], 1.0 op_sel_hi:[1,0]
	v_pk_add_f32 v[62:63], v[110:111], 1.0 op_sel_hi:[1,0]
	s_waitcnt vmcnt(0)
	v_pk_fma_f32 v[60:61], v[50:51], v[60:61], v[116:117]
	v_pk_fma_f32 v[50:51], v[48:49], v[62:63], v[114:115]
	v_cvt_pk_bf16_f32 v48, v52, v53
	v_cvt_pk_bf16_f32 v49, v54, v55
	s_nop 0
	v_cvt_pk_bf16_f32 v50, v50, v51
	v_cvt_pk_bf16_f32 v51, v60, v61
	s_mov_b64 s[76:77], 0x4000
	v_lshl_add_u64 v[118:119], v[118:119], 0, s[76:77]
	global_store_dwordx4 v[118:119], v[48:51], off sc1
	s_and_saveexec_b64 s[64:65], s[4:5]
	s_cbranch_execnz .LBB0_145
	s_or_b64 exec, exec, s[64:65]
	s_and_saveexec_b64 s[4:5], s[0:1]
	s_cbranch_execnz .LBB0_146

; __device__ __forceinline__ int fresh_tid() { int t = threadIdx.x; asm volatile("" : "+v"(t)); return t; }
; template <class Epi>
; __device__ __forceinline__ void small_gemm(const bf16_t* __restrict__ A, int nm16, const bf16_t* __restrict__ Bt, int N, int K, const Epi& E, int row_base, float* smem, int blk, int nblk) {
;     if (blk < 0) return;
;     const int tid = fresh_tid(), w = tid >> 6, lane = tid & 63, fr = lane & 15, fq = lane >> 4;
;     const int ntasks = (N / 256) * 4 * nm16, kw = K / 8;
;     f32x4* red = (f32x4*)smem;
;     for (int t = blk; t < ntasks; t += nblk) {
;         const int m16 = t % nm16, r = t / nm16, wc = r & 3, pn = r >> 2;
;         const bf16_t* ap = A + (size_t)(m16 * 16 + fr) * K + w * kw + fq * 8;
;         const bf16_t* bp = Bt + (size_t)(pn * 256 + wc * 32 + fr) * K + w * kw + fq * 8;
.LBB0_363:
	s_add_u32 s14, s58, 0x3a70000
	s_addc_u32 s15, s59, 0
	s_add_i32 s6, s2, 0xffffff80
	s_cmpk_eq_i32 s34, 0x100
	s_cselect_b64 s[0:1], -1, 0
	s_and_b64 s[4:5], s[0:1], exec
	s_cselect_b32 s12, s6, s2
	s_cmp_lt_i32 s12, 0
	s_cbranch_scc1 .LBB0_391
	v_mov_b32_e32 v0, v224
	s_cmpk_gt_u32 s12, 0x13f
	s_cbranch_scc1 .LBB0_391
	s_and_b64 s[0:1], s[0:1], exec
	v_ashrrev_i32_e32 v6, 6, v0
	s_cselect_b32 s13, 0x80, s34
	v_lshlrev_b32_e32 v2, 7, v6
	s_add_u32 s6, s56, 0x4088000
	v_ashrrev_i32_e32 v3, 31, v2
	v_lshrrev_b32_e32 v7, 1, v0
	s_addc_u32 s7, s57, 0
	v_and_b32_e32 v9, 15, v0
	v_lshlrev_b64 v[2:3], 1, v[2:3]
	v_and_b32_e32 v8, 24, v7
	s_add_u32 s8, s56, 0x4080000
	v_and_b32_e32 v1, 63, v0
	v_lshl_add_u64 v[4:5], s[14:15], 0, v[2:3]
	v_mov_b32_e32 v11, 0
	v_lshlrev_b32_e32 v10, 1, v8
	v_lshl_add_u64 v[2:3], s[58:59], 0, v[2:3]
	v_cmp_gt_u32_e64 s[4:5], 64, v0
	v_lshl_add_u32 v50, v0, 4, 16
	s_addc_u32 s9, s57, 0
	s_lshl_b32 s0, s12, 4
	s_lshl_b32 s1, s12, 5
	v_lshlrev_b32_e32 v0, 1, v9
	v_lshl_add_u32 v1, v1, 4, 16
	v_lshl_add_u64 v[14:15], v[2:3], 0, v[10:11]
	v_lshlrev_b32_e32 v2, 12, v6
	v_or3_b32 v51, s1, v0, 1
	v_or_b32_e32 v0, s0, v9
	v_mov_b32_e32 v3, 0x800000
	s_movk_i32 s52, 0xf400
	v_lshl_add_u64 v[12:13], v[4:5], 0, v[10:11]
	v_and_b32_e32 v94, 63, v224
	v_lshlrev_b32_e32 v94, 4, v94
	v_ashrrev_i32_e32 v95, 6, v224
	v_lshl_add_u32 v94, v95, 12, v94
	v_mov_b32_e32 v95, 0
	v_lshl_add_u64 v[94:95], s[14:15], 0, v[94:95]
	s_add_i32 s33, s0, 0x4000
	s_lshl_b32 s60, s13, 4
	s_lshl_b32 s61, s13, 5
	s_mov_b32 s72, 0x800000
	v_lshl_add_u32 v52, v0, 9, v3
	s_lshl_b32 s73, s13, 13
	s_mov_b32 s11, 0
	s_mov_b32 s74, 0x8000
	s_mov_b32 s75, 0x40000
	s_mov_b32 s76, 0x48000
	v_add_u32_e32 v53, v1, v2
	s_movk_i32 s77, 0x3fff
	s_mov_b32 s53, -1
	s_movk_i32 s78, 0x7fd
	v_mov_b32_e32 v54, 0x358637bd
	s_mov_b64 s[64:65], 0x2108000
	s_branch .LBB0_368

; template <class Epi>
; __device__ __forceinline__ void small_gemm(const bf16_t* __restrict__ A, int nm16, const bf16_t* __restrict__ Bt, int N, int K, const Epi& E, int row_base, float* smem, int blk, int nblk) {
;     ...
;     for (int t = blk; t < ntasks; t += nblk) {
;         const int m16 = t % nm16, r = t / nm16, wc = r & 3, pn = r >> 2;
;         const bf16_t* ap = A + (size_t)(m16 * 16 + fr) * K + w * kw + fq * 8;
;         const bf16_t* bp = Bt + (size_t)(pn * 256 + wc * 32 + fr) * K + w * kw + fq * 8;
;         f32x4 acc[2][2] = {{{0.f, 0.f, 0.f, 0.f}, {0.f, 0.f, 0.f, 0.f}}, {{0.f, 0.f, 0.f, 0.f}, {0.f, 0.f, 0.f, 0.f}}};
; #pragma unroll 4
;         for (int ks = 0; ks < kw / 32; ++ks) {
;             Frag a; a.q = *(const uint4*)(ap + ks * 32);
; #pragma unroll
;             for (int bj = 0; bj < 2; ++bj)
; #pragma unroll
;                 for (int n = 0; n < 2; ++n) { Frag b; b.q = *(const uint4*)(bp + (size_t)(bj * 128 + n * 16) * K + ks * 32);
;                     acc[bj][n] = __builtin_amdgcn_mfma_f32_16x16x32_bf16(b.v, a.v, acc[bj][n], 0, 0, 0); }
;         }
; #pragma unroll
;         for (int i = 0; i < 4; ++i) red[(w * 4 + i) * 64 + lane] = acc[i >> 1][i & 1];
.LBB0_368:
	s_ashr_i32 s0, s12, 31
	s_lshr_b32 s0, s0, 29
	s_add_i32 s0, s12, s0
	s_ashr_i32 s80, s0, 3
	s_and_b32 s81, s80, 3
	s_ashr_i32 s70, s0, 5
	s_lshl_b32 s79, s81, 5
	s_lshl_b32 s10, s70, 8
	v_or_b32_e32 v0, s79, v9
	v_or_b32_e32 v0, s10, v0
	v_ashrrev_i32_e32 v1, 31, v0
	s_lshl_b32 s71, s80, 7
	v_lshlrev_b64 v[0:1], 11, v[0:1]
	s_sub_i32 s0, s33, s71
	v_lshl_add_u64 v[60:61], v[14:15], 0, v[0:1]
	v_add_u32_e32 v16, s0, v9
	v_add_co_u32_e32 v64, vcc, s74, v60
	v_add_u32_e32 v4, 0xffffc000, v16
	s_nop 0
	v_addc_co_u32_e32 v65, vcc, 0, v61, vcc
	v_ashrrev_i32_e32 v5, 31, v4
	v_add_co_u32_e32 v66, vcc, s75, v60
	v_lshlrev_b64 v[4:5], 11, v[4:5]
	s_nop 0
	v_addc_co_u32_e32 v67, vcc, 0, v61, vcc
	v_and_b32_e32 v4, 0xffff8000, v4
	v_lshl_add_u64 v[62:63], v[94:95], 0, v[4:5]
	v_add_co_u32_e32 v68, vcc, s76, v60
	s_nop 1
	v_addc_co_u32_e32 v69, vcc, 0, v61, vcc
	global_load_dwordx4 v[96:99], v[62:63], off
	global_load_dwordx4 v[112:115], v[60:61], off
	global_load_dwordx4 v[128:131], v[64:65], off
	global_load_dwordx4 v[168:171], v[66:67], off
	global_load_dwordx4 v[196:199], v[68:69], off
	global_load_dwordx4 v[100:103], v[62:63], off offset:1024
	global_load_dwordx4 v[116:119], v[60:61], off offset:64
	global_load_dwordx4 v[132:135], v[64:65], off offset:64
	global_load_dwordx4 v[172:175], v[66:67], off offset:64
	global_load_dwordx4 v[200:203], v[68:69], off offset:64
	global_load_dwordx4 v[104:107], v[62:63], off offset:2048
	global_load_dwordx4 v[120:123], v[60:61], off offset:128
	global_load_dwordx4 v[160:163], v[64:65], off offset:128
	global_load_dwordx4 v[176:179], v[66:67], off offset:128
	global_load_dwordx4 v[204:207], v[68:69], off offset:128
	global_load_dwordx4 v[108:111], v[62:63], off offset:3072
	global_load_dwordx4 v[124:127], v[60:61], off offset:192
	global_load_dwordx4 v[164:167], v[64:65], off offset:192
	global_load_dwordx4 v[192:195], v[66:67], off offset:192
	global_load_dwordx4 v[208:211], v[68:69], off offset:192
	s_waitcnt vmcnt(15)
	v_mfma_f32_16x16x32_bf16 v[0:3], v[112:115], v[96:99], 0
	v_mfma_f32_16x16x32_bf16 v[18:21], v[128:131], v[96:99], 0
	v_mfma_f32_16x16x32_bf16 v[22:25], v[168:171], v[96:99], 0
	v_mfma_f32_16x16x32_bf16 v[4:7], v[196:199], v[96:99], 0
	s_waitcnt vmcnt(10)
	v_mfma_f32_16x16x32_bf16 v[0:3], v[116:119], v[100:103], v[0:3]
	v_mfma_f32_16x16x32_bf16 v[18:21], v[132:135], v[100:103], v[18:21]
	v_mfma_f32_16x16x32_bf16 v[22:25], v[172:175], v[100:103], v[22:25]
	v_mfma_f32_16x16x32_bf16 v[4:7], v[200:203], v[100:103], v[4:7]
	s_waitcnt vmcnt(5)
	v_mfma_f32_16x16x32_bf16 v[0:3], v[120:123], v[104:107], v[0:3]
	v_mfma_f32_16x16x32_bf16 v[18:21], v[160:163], v[104:107], v[18:21]
	v_mfma_f32_16x16x32_bf16 v[22:25], v[176:179], v[104:107], v[22:25]
	v_mfma_f32_16x16x32_bf16 v[4:7], v[204:207], v[104:107], v[4:7]
	s_waitcnt vmcnt(0)
	v_mfma_f32_16x16x32_bf16 v[0:3], v[124:127], v[108:111], v[0:3]
	v_mfma_f32_16x16x32_bf16 v[18:21], v[164:167], v[108:111], v[18:21]
	v_mfma_f32_16x16x32_bf16 v[22:25], v[192:195], v[108:111], v[22:25]
	v_mfma_f32_16x16x32_bf16 v[4:7], v[208:211], v[108:111], v[4:7]
	s_nop 7
	s_nop 3
	ds_write_b128 v53, v[0:3]
	s_nop 0
	ds_write_b128 v53, v[18:21] offset:1024
	ds_write_b128 v53, v[22:25] offset:2048
	ds_write_b128 v53, v[4:7] offset:3072
	s_waitcnt lgkmcnt(0)
	s_barrier
	s_and_saveexec_b64 s[66:67], s[4:5]
	s_cbranch_execz .LBB0_367
; __device__ __forceinline__ void st_bf16x8(bf16_t* p, const f32x4 a, const f32x4 b) { uint4 o; o.x = cvt_pk_bf16(a[0], a[1]); o.y = cvt_pk_bf16(a[2], a[3]); o.z = cvt_pk_bf16(b[0], b[1]); o.w = cvt_pk_bf16(b[2], b[3]); *(uint4*)p = o; }
;     __device__ __forceinline__ void row(const f32x4 (&a)[2][2], int row, int pn, int wc, int fq) const {
;     ...
;             const int c = (pn - 6) * 128 + wc * 32 + 8 * fq;
;             const f32x4 z0 = a[0][0] * a[1][0], z1 = a[0][1] * a[1][1];
;             st_bf16x8(pZ + (size_t)row * 512 + c, z0, z1);
;             float* o = nullptr;
;             if (row < NP) { const int t = row & 2047; if (t >= 2046) o = out + O_CONVP + (size_t)((row >> 11) * 2 + (t - 2046)) * 512 + c; }
;             else if (row < NTOK) o = out + O_CONVS + (size_t)((row - NP) * 2 + 1) * 512 + c;
;             if (o) { *(f32x4*)o = z0; *(f32x4*)(o + 4) = z1; }
; template <class Epi>
; __device__ __forceinline__ void small_gemm(const bf16_t* __restrict__ A, int nm16, const bf16_t* __restrict__ Bt, int N, int K, const Epi& E, int row_base, float* smem, int blk, int nblk) {
;     ...
;         for (int i = 0; i < 4; ++i) red[(w * 4 + i) * 64 + lane] = acc[i >> 1][i & 1];
;         __syncthreads();
;         if (w == 0) { f32x4 s[2][2];
; #pragma unroll
;             for (int i = 0; i < 4; ++i) { f32x4 v = red[i * 64 + lane];
; #pragma unroll
;                 for (int w2 = 1; w2 < 8; ++w2) v += red[(w2 * 4 + i) * 64 + lane];
;                 s[i >> 1][i & 1] = v; }
;             E.row(s, row_base + m16 * 16 + fr, pn, wc, fq); }
	ds_read_b128 v[0:3], v50
	ds_read_b128 v[4:7], v50 offset:4096
	ds_read_b128 v[18:21], v50 offset:8192
	ds_read_b128 v[22:25], v50 offset:1024
	ds_read_b128 v[30:33], v50 offset:5120
	s_cmp_lt_i32 s70, 2
	s_waitcnt lgkmcnt(3)
	v_pk_add_f32 v[26:27], v[2:3], v[6:7]
	v_pk_add_f32 v[28:29], v[0:1], v[4:5]
	ds_read_b128 v[0:3], v50 offset:12288
	ds_read_b128 v[4:7], v50 offset:9216
	s_waitcnt lgkmcnt(4)
	v_pk_add_f32 v[26:27], v[26:27], v[20:21]
	v_pk_add_f32 v[28:29], v[28:29], v[18:19]
	ds_read_b128 v[18:21], v50 offset:16384
	ds_read_b128 v[34:37], v50 offset:13312
	s_waitcnt lgkmcnt(3)
	v_pk_add_f32 v[26:27], v[26:27], v[2:3]
	v_pk_add_f32 v[28:29], v[28:29], v[0:1]
	ds_read_b128 v[0:3], v50 offset:20480
	ds_read_b128 v[38:41], v50 offset:17408
	s_waitcnt lgkmcnt(3)
	v_pk_add_f32 v[26:27], v[26:27], v[20:21]
	v_pk_add_f32 v[28:29], v[28:29], v[18:19]
	ds_read_b128 v[18:21], v50 offset:24576
	ds_read_b128 v[42:45], v50 offset:21504
	s_waitcnt lgkmcnt(3)
	v_pk_add_f32 v[26:27], v[26:27], v[2:3]
	v_pk_add_f32 v[28:29], v[28:29], v[0:1]
	ds_read_b128 v[0:3], v50 offset:28672
	ds_read_b128 v[46:49], v50 offset:25600
	s_waitcnt lgkmcnt(3)
	v_pk_add_f32 v[28:29], v[28:29], v[18:19]
	v_pk_add_f32 v[26:27], v[26:27], v[20:21]
	ds_read_b128 v[18:21], v50 offset:29696
	s_waitcnt lgkmcnt(2)
	v_pk_add_f32 v[28:29], v[28:29], v[0:1]
	v_pk_add_f32 v[0:1], v[24:25], v[32:33]
	v_pk_add_f32 v[26:27], v[26:27], v[2:3]
	v_pk_add_f32 v[2:3], v[22:23], v[30:31]
	v_pk_add_f32 v[0:1], v[0:1], v[6:7]
	v_pk_add_f32 v[2:3], v[2:3], v[4:5]
	v_pk_add_f32 v[0:1], v[0:1], v[36:37]
	v_pk_add_f32 v[2:3], v[2:3], v[34:35]
	v_pk_add_f32 v[0:1], v[0:1], v[40:41]
	v_pk_add_f32 v[2:3], v[2:3], v[38:39]
	v_pk_add_f32 v[0:1], v[0:1], v[44:45]
	v_pk_add_f32 v[2:3], v[2:3], v[42:43]
	s_waitcnt lgkmcnt(1)
	v_pk_add_f32 v[0:1], v[0:1], v[48:49]
	v_pk_add_f32 v[22:23], v[2:3], v[46:47]
	s_waitcnt lgkmcnt(0)
	v_pk_add_f32 v[30:31], v[0:1], v[20:21]
	ds_read_b128 v[0:3], v50 offset:2048
	ds_read_b128 v[4:7], v50 offset:6144
	v_pk_add_f32 v[32:33], v[22:23], v[18:19]
	ds_read_b128 v[18:21], v50 offset:10240
	ds_read_b128 v[22:25], v50 offset:3072
	ds_read_b128 v[34:37], v50 offset:7168
	s_cselect_b64 s[68:69], -1, 0
	s_cmp_gt_i32 s70, 1
	s_waitcnt lgkmcnt(3)
	v_pk_add_f32 v[38:39], v[2:3], v[6:7]
	v_pk_add_f32 v[40:41], v[0:1], v[4:5]
	ds_read_b128 v[0:3], v50 offset:14336
	ds_read_b128 v[4:7], v50 offset:11264
	s_waitcnt lgkmcnt(4)
	v_pk_add_f32 v[42:43], v[38:39], v[20:21]
	v_pk_add_f32 v[44:45], v[40:41], v[18:19]
	ds_read_b128 v[18:21], v50 offset:18432
	ds_read_b128 v[38:41], v50 offset:15360
	s_waitcnt lgkmcnt(3)
	v_pk_add_f32 v[46:47], v[42:43], v[2:3]
	v_pk_add_f32 v[48:49], v[44:45], v[0:1]
	ds_read_b128 v[0:3], v50 offset:22528
	ds_read_b128 v[42:45], v50 offset:19456
	s_waitcnt lgkmcnt(3)
	v_pk_add_f32 v[56:57], v[46:47], v[20:21]
	v_pk_add_f32 v[58:59], v[48:49], v[18:19]
	ds_read_b128 v[18:21], v50 offset:26624
	ds_read_b128 v[46:49], v50 offset:23552
	s_waitcnt lgkmcnt(3)
	v_pk_add_f32 v[60:61], v[56:57], v[2:3]
	v_pk_add_f32 v[62:63], v[58:59], v[0:1]
	ds_read_b128 v[0:3], v50 offset:30720
	ds_read_b128 v[56:59], v50 offset:27648
	s_waitcnt lgkmcnt(3)
	v_pk_add_f32 v[20:21], v[60:61], v[20:21]
	v_pk_add_f32 v[64:65], v[62:63], v[18:19]
	ds_read_b128 v[60:63], v50 offset:31744
	s_waitcnt lgkmcnt(2)
	v_pk_add_f32 v[18:19], v[20:21], v[2:3]
	v_pk_add_f32 v[20:21], v[64:65], v[0:1]
	v_pk_add_f32 v[0:1], v[24:25], v[36:37]
	v_pk_add_f32 v[2:3], v[22:23], v[34:35]
	v_pk_add_f32 v[0:1], v[0:1], v[6:7]
	v_pk_add_f32 v[2:3], v[2:3], v[4:5]
	v_pk_add_f32 v[0:1], v[0:1], v[40:41]
	v_pk_add_f32 v[2:3], v[2:3], v[38:39]
	s_cselect_b64 s[0:1], -1, 0
	s_and_b32 s82, s80, -8
	v_pk_add_f32 v[0:1], v[0:1], v[44:45]
	v_pk_add_f32 v[2:3], v[2:3], v[42:43]
	s_cmp_lg_u32 s82, 16
	v_pk_add_f32 v[0:1], v[0:1], v[48:49]
	v_pk_add_f32 v[2:3], v[2:3], v[46:47]
	s_cselect_b64 s[82:83], -1, 0
	s_waitcnt lgkmcnt(1)
	v_pk_add_f32 v[0:1], v[0:1], v[58:59]
	v_pk_add_f32 v[2:3], v[2:3], v[56:57]
	s_and_b64 s[82:83], s[0:1], s[82:83]
	s_waitcnt lgkmcnt(0)
	v_pk_add_f32 v[22:23], v[0:1], v[62:63]
	v_pk_add_f32 v[24:25], v[2:3], v[60:61]
	s_mov_b64 s[0:1], -1
	s_and_b64 vcc, exec, s[82:83]
	s_cbranch_vccz .LBB0_382
	s_sub_i32 s0, 0, s71
	s_add_i32 s82, s33, s0
	s_cmp_gt_u32 s70, 3
	s_mov_b64 s[0:1], -1
	s_cbranch_scc0 .LBB0_376
	s_lshl_b32 s0, s70, 7
	v_mov_b32_e32 v17, v11
	v_lshlrev_b64 v[34:35], 10, v[16:17]
	s_or_b32 s0, s0, s79
	v_lshl_add_u64 v[34:35], s[50:51], 0, v[34:35]
	v_add_u32_e32 v10, s0, v8
	v_pk_mul_f32 v[2:3], v[26:27], v[18:19]
	v_pk_mul_f32 v[0:1], v[28:29], v[20:21]
	v_pk_mul_f32 v[6:7], v[30:31], v[22:23]
	v_pk_mul_f32 v[4:5], v[32:33], v[24:25]
	v_lshl_add_u64 v[38:39], v[10:11], 1, v[34:35]
	v_cvt_pk_bf16_f32 v34, v0, v1
	v_cvt_pk_bf16_f32 v35, v2, v3
	v_cmp_lt_i32_e32 vcc, s77, v16
	v_cvt_pk_bf16_f32 v36, v4, v5
	v_cvt_pk_bf16_f32 v37, v6, v7
	global_store_dwordx4 v[38:39], v[34:37], off offset:-1536
	s_and_saveexec_b64 s[0:1], vcc
	s_xor_b64 s[0:1], exec, s[0:1]
	s_cbranch_execnz .LBB0_387
	s_andn2_saveexec_b64 s[0:1], s[0:1]
	s_cbranch_execnz .LBB0_388
